# weight conversions moved: convert_ffn(L) to before the barrier after the projection phase, convert_mixer(L+1) to before the barrier after FFN-up (they overlap the phase tail instead of starting a half
# baseline (speedup 1.0000x reference)
.LBB0_162:
	s_lshr_b32 s56, s40, 1
	s_and_b32 s4, s40, 2
	s_cmp_eq_u32 s4, 0
	s_cselect_b64 s[90:91], -1, 0
	s_cmp_lg_u32 s4, 0
	s_cselect_b64 s[58:59], -1, 0
	s_and_b32 s4, s40, 1
	s_cmp_eq_u32 s4, 0
	s_cselect_b64 s[6:7], -1, 0
	v_writelane_b32 v255, s6, 39
	s_cmp_eq_u32 s4, 1
	s_cselect_b64 s[4:5], -1, 0
	v_writelane_b32 v255, s7, 40
	v_writelane_b32 v255, s4, 41
	s_and_b64 vcc, exec, s[4:5]
	s_nop 0
	v_writelane_b32 v255, s5, 42
	s_mov_b64 s[4:5], -1
	s_cbranch_vccz .LBB0_542
.LBB0_442:
	v_readlane_b32 s6, v254, 5
	v_readlane_b32 s7, v254, 6
	v_mov_b32_e32 v17, v237
	s_mov_b64 s[8:9], 0
	v_cndmask_b32_e64 v0, 0, 1, s[6:7]
	v_readfirstlane_b32 s10, v17
	v_cmp_ne_u32_e64 s[4:5], 1, v0
	s_andn2_b64 vcc, exec, s[6:7]
	s_mov_b64 s[6:7], 0
	s_cbranch_vccnz .LBB0_444
	v_readlane_b32 s8, v254, 58
	v_readlane_b32 s6, v254, 56
	v_readlane_b32 s9, v254, 59
	v_readlane_b32 s7, v254, 57
	v_readlane_b32 s68, v254, 55
	v_readlane_b32 s73, v254, 54

.LBB0_489:
	s_cmp_gt_u32 s40, 5
	s_cbranch_scc1 .Lmy_cvm_skip
	v_mov_b32_e32 v37, v237
	v_readlane_b32 s6, v254, 0
	v_readfirstlane_b32 s5, v37
	s_ashr_i32 s5, s5, 6
	s_add_i32 s12, s5, s6
	s_load_dwordx2 s[6:7], s[0:1], 0x80
	s_add_i32 s4, s56, 1
	s_lshl_b32 s5, s5, 14
	s_add_i32 s13, s5, 0
	s_lshr_b32 s42, s4, 1
	s_lshl_b32 s4, s4, 12
	s_waitcnt lgkmcnt(0)
	s_add_u32 s6, s6, s4
	v_and_b32_e32 v36, 63, v37
	s_addc_u32 s7, s7, 0
	s_andn2_b64 vcc, exec, s[58:59]
	s_mov_b64 s[4:5], -1
	s_cbranch_vccnz .LBB0_301
	s_load_dwordx2 s[8:9], s[0:1], 0x8
	s_mul_i32 s5, s42, 0x600000
	s_mul_hi_u32 s4, s42, 0x600000
	s_waitcnt lgkmcnt(0)
	s_add_u32 s14, s8, s5
	s_addc_u32 s15, s9, s4
	s_load_dwordx2 s[8:9], s[0:1], 0x20
	s_lshl_b64 s[4:5], s[42:43], 22
	s_waitcnt lgkmcnt(0)
	s_add_u32 s16, s8, s4
	s_addc_u32 s17, s9, s5
	s_cmpk_lt_i32 s12, 0x500
	s_cselect_b64 s[8:9], -1, 0
	s_cmpk_gt_i32 s12, 0x4ff
	s_cbranch_scc1 .LBB0_231
	s_cmpk_gt_i32 s12, 0x2ff
	s_cselect_b64 s[4:5], -1, 0
	s_and_b64 s[10:11], s[4:5], exec
	s_movk_i32 s10, 0x600
	s_cselect_b32 s18, 0x400, s10
	s_cselect_b32 s20, 0xfffffd00, 0
	s_lshr_b32 s19, s18, 5
	s_abs_i32 s10, s19
	v_cvt_f32_u32_e32 v0, s10
	s_sub_i32 s22, 0, s10
	s_add_i32 s20, s20, s12
	s_abs_i32 s21, s20
	v_rcp_iflag_f32_e32 v0, v0
	s_xor_b32 s11, s20, s19
	s_ashr_i32 s11, s11, 31
	v_lshrrev_b32_e32 v2, 5, v36
	v_mul_f32_e32 v0, 0x4f7ffffe, v0
	v_cvt_u32_f32_e32 v0, v0
	v_mov_b32_e32 v8, 1.0
	v_readfirstlane_b32 s23, v0
	s_mul_i32 s22, s22, s23
	s_mul_hi_u32 s22, s23, s22
	s_add_i32 s23, s23, s22
	s_mul_hi_u32 s22, s21, s23
	s_mul_i32 s23, s22, s10
	s_sub_i32 s21, s21, s23
	s_add_i32 s24, s22, 1
	s_sub_i32 s23, s21, s10
	s_cmp_ge_u32 s21, s10
	s_cselect_b32 s22, s24, s22
	s_cselect_b32 s21, s23, s21
	s_add_i32 s23, s22, 1
	s_cmp_ge_u32 s21, s10
	s_cselect_b32 s10, s23, s22
	s_xor_b32 s10, s10, s11
	s_sub_i32 s21, s10, s11
	v_lshl_or_b32 v2, s21, 6, v2
	s_or_b64 s[10:11], s[4:5], s[92:93]
	v_ashrrev_i32_e32 v3, 31, v2
	s_and_b64 vcc, exec, s[10:11]
	v_lshl_add_u64 v[6:7], v[2:3], 2, s[6:7]
	v_mov_b32_e32 v3, 1.0
	s_cbranch_vccnz .LBB0_168
	global_load_dword v3, v[6:7], off

.LBB0_542:
	v_readlane_b32 s12, v254, 46
	s_and_b64 vcc, exec, s[4:5]
	v_readlane_b32 s13, v254, 47
	s_cbranch_vccz .LBB0_1027
.LBB0_680:
	s_and_b64 s[4:5], s[90:91], exec
	s_cselect_b32 s15, 5, 12
	s_cselect_b32 s54, 1, 12
	s_lshl_b32 s16, s15, 7
	s_and_b64 s[4:5], s[90:91], exec
	s_cselect_b32 s42, 0x300, s95
	v_mov_b32_e32 v14, v237
	s_cmp_lt_i32 s2, s42
	s_barrier
	s_movk_i32 s22, 0xc00
	v_readfirstlane_b32 s12, v14
	s_mov_b64 s[6:7], 0
	s_cselect_b64 s[4:5], -1, 0
	s_cmp_ge_i32 s2, s42
	s_mov_b64 s[8:9], 0
	s_cbranch_scc1 .LBB0_690
	s_cmp_ge_i32 s2, s16
	s_mov_b64 s[6:7], -1
	s_cbranch_scc0 .LBB0_683
	s_sub_i32 s6, s2, s16
	v_readlane_b32 s7, v254, 17
	s_mul_i32 s8, s7, s54
	s_lshr_b32 s9, s6, 3
	s_mov_b64 s[6:7], 0

.LBB0_854:
	v_mov_b32_e32 v35, v237
	s_mul_i32 s7, s56, 0x1600000
	v_readfirstlane_b32 s4, v35
	s_ashr_i32 s19, s4, 6
	v_readlane_b32 s4, v254, 0
	s_add_i32 s18, s19, s4
	s_load_dwordx2 s[4:5], s[0:1], 0x60
	s_load_dwordx2 s[10:11], s[0:1], 0x78
	s_load_dwordx2 s[8:9], s[0:1], 0x90
	s_mov_b32 s57, s43
	s_mul_hi_u32 s6, s56, 0x1600000
	v_and_b32_e32 v34, 63, v35
	s_waitcnt lgkmcnt(0)
	s_add_u32 s14, s4, s7
	s_addc_u32 s15, s5, s6
	s_lshl_b64 s[4:5], s[56:57], 12
	s_add_u32 s6, s8, s4
	s_addc_u32 s7, s9, s5
	s_mul_i32 s5, s56, 0xb00000
	s_mul_hi_u32 s4, s56, 0xb00000
	s_add_u32 s16, s10, s5
	s_addc_u32 s17, s11, s4
	s_cmpk_lt_i32 s18, 0x1080
	s_cselect_b64 s[10:11], -1, 0
	s_cmpk_gt_i32 s18, 0x107f
	v_lshrrev_b32_e32 v36, 5, v34
	s_cbranch_scc1 .LBB0_609
	s_cmpk_gt_i32 s18, 0xaff
	s_cselect_b64 s[4:5], -1, 0
	s_and_b64 s[12:13], s[4:5], exec
	s_cselect_b32 s20, 0x400, s3
	s_cselect_b32 s22, 0xfffff500, 0
	s_lshr_b32 s21, s20, 5
	s_abs_i32 s12, s21
	v_cvt_f32_u32_e32 v0, s12
	s_sub_i32 s24, 0, s12
	s_add_i32 s22, s22, s18
	s_abs_i32 s23, s22
	v_rcp_iflag_f32_e32 v0, v0
	s_xor_b32 s13, s22, s21
	s_ashr_i32 s13, s13, 31
	v_mov_b32_e32 v8, 1.0
	v_mul_f32_e32 v0, 0x4f7ffffe, v0
	v_cvt_u32_f32_e32 v0, v0
	s_nop 0
	v_readfirstlane_b32 s25, v0
	s_mul_i32 s24, s24, s25
	s_mul_hi_u32 s24, s25, s24
	s_add_i32 s25, s25, s24
	s_mul_hi_u32 s24, s23, s25
	s_mul_i32 s25, s24, s12
	s_sub_i32 s23, s23, s25
	s_add_i32 s26, s24, 1
	s_sub_i32 s25, s23, s12
	s_cmp_ge_u32 s23, s12
	s_cselect_b32 s24, s26, s24
	s_cselect_b32 s23, s25, s23
	s_add_i32 s25, s24, 1
	s_cmp_ge_u32 s23, s12
	s_cselect_b32 s12, s25, s24
	s_xor_b32 s12, s12, s13
	s_sub_i32 s23, s12, s13
	s_cmp_eq_u64 s[8:9], 0
	v_lshl_or_b32 v2, s23, 6, v36
	s_cselect_b64 s[12:13], -1, 0
	s_or_b64 s[12:13], s[4:5], s[12:13]
	v_ashrrev_i32_e32 v3, 31, v2
	s_and_b64 vcc, exec, s[12:13]
	v_lshl_add_u64 v[6:7], v[2:3], 2, s[6:7]
	v_mov_b32_e32 v3, 1.0
	s_cbranch_vccnz .LBB0_546
	global_load_dword v3, v[6:7], off

.LBB0_678:
	s_cmpk_lt_i32 s18, 0xb00
	s_cselect_b64 s[4:5], -1, 0
	s_and_b64 s[12:13], s[4:5], exec
	s_cselect_b32 s12, 0xb0, 32
	v_cvt_f32_ubyte0_e32 v35, s12
	v_rcp_iflag_f32_e32 v35, v35
	s_cselect_b32 s13, 0, 0xfffff500
	s_add_i32 s20, s13, s18
	s_sub_i32 s13, 0, s12
	v_mul_f32_e32 v35, 0x4f7ffffe, v35
	v_cvt_u32_f32_e32 v35, v35
	s_abs_i32 s22, s20
	s_ashr_i32 s21, s20, 31
	s_waitcnt lgkmcnt(0)
	v_readfirstlane_b32 s23, v35
	s_mul_i32 s13, s13, s23
	s_mul_hi_u32 s13, s23, s13
	s_add_i32 s23, s23, s13
	s_mul_hi_u32 s13, s22, s23
	s_mul_i32 s23, s13, s12
	s_sub_i32 s22, s22, s23
	s_add_i32 s24, s13, 1
	s_sub_i32 s23, s22, s12
	s_cmp_ge_u32 s22, s12
	s_cselect_b32 s13, s24, s13
	s_cselect_b32 s22, s23, s22
	s_add_i32 s23, s13, 1
	s_cmp_ge_u32 s22, s12
	s_cselect_b32 s13, s23, s13
	s_xor_b32 s13, s13, s21
	s_sub_i32 s13, s13, s21
	s_mul_i32 s12, s13, s12
	s_sub_i32 s20, s20, s12
	s_lshl_b32 s12, s20, 5
	s_cmpk_gt_i32 s18, 0xaff
	s_cbranch_scc1 .LBB0_611
	s_add_i32 s18, s12, 0xfffff500
	s_cmpk_lt_i32 s20, 0x58
	s_cselect_b32 s12, s12, s18
	s_cselect_b32 s18, 0, 0x80
	s_lshl_b32 s20, s12, 1
	s_and_b32 s12, s12, 0x60
	s_and_b32 s20, s20, 0xffffff00
	s_or_b32 s12, s12, s18
	s_or_b32 s12, s12, s20
	s_branch .LBB0_611
.Lmy_cvf_end:
	s_getreg_b32 s6, hwreg(HW_REG_XCC_ID, 0, 4)
	s_waitcnt vmcnt(0)
	s_waitcnt vmcnt(0)
	s_barrier
	s_and_saveexec_b64 s[4:5], s[74:75]
	v_readlane_b32 s26, v254, 28
	v_readlane_b32 s57, v254, 29
	v_readlane_b32 s68, v254, 30
	v_readlane_b32 s69, v255, 7
	v_readlane_b32 s72, v255, 8
	s_mov_b32 s27, 0x600000
	s_movk_i32 s95, 0xc00
	s_cbranch_execz .LBB0_906
	v_readlane_b32 s7, v255, 10
	v_readlane_b32 s8, v255, 11
	s_and_b32 s6, s6, 15
	s_lshl_b32 s6, s6, 8
	v_mov_b32_e32 v0, s7
	v_mov_b32_e32 v2, s8
	ds_read_b32 v3, v0
	ds_read_b32 v2, v2
	s_add_i32 s9, s6, 0x1400
	s_add_i32 s10, s6, 0x4000
	s_waitcnt vmcnt(0) lgkmcnt(0)
	v_cmp_ne_u32_e32 vcc, 0, v3
	s_cbranch_vccnz .Lmy_xb1_have
	s_mov_b32 s12, 0
